# stagger the start of the two FFN up-projection GEMM phases by XCD slot (1.5us steps)
# speedup vs baseline: 1.0290x; 1.0290x over previous
.LBB0_332:
	s_or_b64 exec, exec, s[6:7]
	s_waitcnt lgkmcnt(0)
	s_lshl_b64 s[4:5], s[14:15], 11
	v_ashrrev_i32_e32 v64, 5, v177
	v_lshl_add_u32 v67, v64, 4, v179
	ds_read2_b32 v[70:71], v67 offset1:1
	ds_read2_b32 v[72:73], v67 offset0:2 offset1:3
	ds_read2_b32 v[74:75], v67 offset0:8 offset1:9
	ds_read2_b32 v[76:77], v67 offset0:10 offset1:11
	ds_read2_b32 v[78:79], v67 offset0:16 offset1:17
	ds_read2_b32 v[80:81], v67 offset0:18 offset1:19
	ds_read2_b32 v[82:83], v67 offset0:24 offset1:25
	ds_read2_b32 v[84:85], v67 offset0:26 offset1:27
	s_add_u32 s4, s10, s4
	s_addc_u32 s5, s11, s5
	s_add_u32 s4, s4, s18
	s_addc_u32 s5, s5, s19
	s_add_i32 s31, s31, 1
	v_readlane_b32 s6, v254, 41
	v_readlane_b32 s7, v254, 42
	v_and_b32_e32 v65, 31, v177
	v_lshlrev_b32_e32 v66, 8, v178
	v_lshl_add_u32 v66, v64, 10, v66
	v_lshl_add_u32 v66, v65, 1, v66
	v_add_u32_e32 v66, 0x11000, v66
	s_waitcnt lgkmcnt(0)
	v_rcp_f32_e32 v70, v70
	v_rcp_f32_e32 v71, v71
	v_rcp_f32_e32 v72, v72
	v_rcp_f32_e32 v73, v73
	v_rcp_f32_e32 v74, v74
	v_rcp_f32_e32 v75, v75
	v_rcp_f32_e32 v76, v76
	v_rcp_f32_e32 v77, v77
	v_rcp_f32_e32 v78, v78
	v_rcp_f32_e32 v79, v79
	v_rcp_f32_e32 v80, v80
	v_rcp_f32_e32 v81, v81
	v_rcp_f32_e32 v82, v82
	v_rcp_f32_e32 v83, v83
	v_rcp_f32_e32 v84, v84
	v_rcp_f32_e32 v85, v85
	s_nop 1
	v_mul_f32_e32 v0, v0, v70
	v_cvt_pk_bf16_f32 v0, v0, v193
	ds_write_b16 v66, v0 offset:0
	v_mul_f32_e32 v48, v48, v70
	v_cvt_pk_bf16_f32 v48, v48, v193
	ds_write_b16 v66, v48 offset:64
	v_mul_f32_e32 v32, v32, v70
	v_cvt_pk_bf16_f32 v32, v32, v193
	ds_write_b16 v66, v32 offset:128
	v_mul_f32_e32 v16, v16, v70
	v_cvt_pk_bf16_f32 v16, v16, v193
	ds_write_b16 v66, v16 offset:192
	v_mul_f32_e32 v1, v1, v71
	v_cvt_pk_bf16_f32 v1, v1, v193
	ds_write_b16 v66, v1 offset:256
	v_mul_f32_e32 v49, v49, v71
	v_cvt_pk_bf16_f32 v49, v49, v193
	ds_write_b16 v66, v49 offset:320
	v_mul_f32_e32 v33, v33, v71
	v_cvt_pk_bf16_f32 v33, v33, v193
	ds_write_b16 v66, v33 offset:384
	v_mul_f32_e32 v17, v17, v71
	v_cvt_pk_bf16_f32 v17, v17, v193
	ds_write_b16 v66, v17 offset:448
	s_waitcnt lgkmcnt(7)
	v_mul_f32_e32 v2, v2, v72
	v_cvt_pk_bf16_f32 v2, v2, v193
	ds_write_b16 v66, v2 offset:512
	v_mul_f32_e32 v50, v50, v72
	v_cvt_pk_bf16_f32 v50, v50, v193
	ds_write_b16 v66, v50 offset:576
	v_mul_f32_e32 v34, v34, v72
	v_cvt_pk_bf16_f32 v34, v34, v193
	ds_write_b16 v66, v34 offset:640
	v_mul_f32_e32 v18, v18, v72
	v_cvt_pk_bf16_f32 v18, v18, v193
	ds_write_b16 v66, v18 offset:704
	v_mul_f32_e32 v3, v3, v73
	v_cvt_pk_bf16_f32 v3, v3, v193
	ds_write_b16 v66, v3 offset:768
	v_mul_f32_e32 v51, v51, v73
	v_cvt_pk_bf16_f32 v51, v51, v193
	ds_write_b16 v66, v51 offset:832
	v_mul_f32_e32 v35, v35, v73
	v_cvt_pk_bf16_f32 v35, v35, v193
	ds_write_b16 v66, v35 offset:896
	v_mul_f32_e32 v19, v19, v73
	v_cvt_pk_bf16_f32 v19, v19, v193
	ds_write_b16 v66, v19 offset:960
	s_waitcnt lgkmcnt(7)
	v_mul_f32_e32 v4, v4, v74
	v_cvt_pk_bf16_f32 v4, v4, v193
	ds_write_b16 v66, v4 offset:2048
	v_mul_f32_e32 v52, v52, v74
	v_cvt_pk_bf16_f32 v52, v52, v193
	ds_write_b16 v66, v52 offset:2112
	v_mul_f32_e32 v36, v36, v74
	v_cvt_pk_bf16_f32 v36, v36, v193
	ds_write_b16 v66, v36 offset:2176
	v_mul_f32_e32 v20, v20, v74
	v_cvt_pk_bf16_f32 v20, v20, v193
	ds_write_b16 v66, v20 offset:2240
	v_mul_f32_e32 v5, v5, v75
	v_cvt_pk_bf16_f32 v5, v5, v193
	ds_write_b16 v66, v5 offset:2304
	v_mul_f32_e32 v53, v53, v75
	v_cvt_pk_bf16_f32 v53, v53, v193
	ds_write_b16 v66, v53 offset:2368
	v_mul_f32_e32 v37, v37, v75
	v_cvt_pk_bf16_f32 v37, v37, v193
	ds_write_b16 v66, v37 offset:2432
	v_mul_f32_e32 v21, v21, v75
	v_cvt_pk_bf16_f32 v21, v21, v193
	ds_write_b16 v66, v21 offset:2496
	s_waitcnt lgkmcnt(7)
	v_mul_f32_e32 v6, v6, v76
	v_cvt_pk_bf16_f32 v6, v6, v193
	ds_write_b16 v66, v6 offset:2560
	v_mul_f32_e32 v54, v54, v76
	v_cvt_pk_bf16_f32 v54, v54, v193
	ds_write_b16 v66, v54 offset:2624
	v_mul_f32_e32 v38, v38, v76
	v_cvt_pk_bf16_f32 v38, v38, v193
	ds_write_b16 v66, v38 offset:2688
	v_mul_f32_e32 v22, v22, v76
	v_cvt_pk_bf16_f32 v22, v22, v193
	ds_write_b16 v66, v22 offset:2752
	v_mul_f32_e32 v7, v7, v77
	v_cvt_pk_bf16_f32 v7, v7, v193
	ds_write_b16 v66, v7 offset:2816
	v_mul_f32_e32 v55, v55, v77
	v_cvt_pk_bf16_f32 v55, v55, v193
	ds_write_b16 v66, v55 offset:2880
	v_mul_f32_e32 v39, v39, v77
	v_cvt_pk_bf16_f32 v39, v39, v193
	ds_write_b16 v66, v39 offset:2944
	v_mul_f32_e32 v23, v23, v77
	v_cvt_pk_bf16_f32 v23, v23, v193
	ds_write_b16 v66, v23 offset:3008
	s_waitcnt lgkmcnt(7)
	v_mul_f32_e32 v8, v8, v78
	v_cvt_pk_bf16_f32 v8, v8, v193
	ds_write_b16 v66, v8 offset:4096
	v_mul_f32_e32 v56, v56, v78
	v_cvt_pk_bf16_f32 v56, v56, v193
	ds_write_b16 v66, v56 offset:4160
	v_mul_f32_e32 v40, v40, v78
	v_cvt_pk_bf16_f32 v40, v40, v193
	ds_write_b16 v66, v40 offset:4224
	v_mul_f32_e32 v24, v24, v78
	v_cvt_pk_bf16_f32 v24, v24, v193
	ds_write_b16 v66, v24 offset:4288
	v_mul_f32_e32 v9, v9, v79
	v_cvt_pk_bf16_f32 v9, v9, v193
	ds_write_b16 v66, v9 offset:4352
	v_mul_f32_e32 v57, v57, v79
	v_cvt_pk_bf16_f32 v57, v57, v193
	ds_write_b16 v66, v57 offset:4416
	v_mul_f32_e32 v41, v41, v79
	v_cvt_pk_bf16_f32 v41, v41, v193
	ds_write_b16 v66, v41 offset:4480
	v_mul_f32_e32 v25, v25, v79
	v_cvt_pk_bf16_f32 v25, v25, v193
	ds_write_b16 v66, v25 offset:4544
	s_waitcnt lgkmcnt(7)
	v_mul_f32_e32 v10, v10, v80
	v_cvt_pk_bf16_f32 v10, v10, v193
	ds_write_b16 v66, v10 offset:4608
	v_mul_f32_e32 v58, v58, v80
	v_cvt_pk_bf16_f32 v58, v58, v193
	ds_write_b16 v66, v58 offset:4672
	v_mul_f32_e32 v42, v42, v80
	v_cvt_pk_bf16_f32 v42, v42, v193
	ds_write_b16 v66, v42 offset:4736
	v_mul_f32_e32 v26, v26, v80
	v_cvt_pk_bf16_f32 v26, v26, v193
	ds_write_b16 v66, v26 offset:4800
	v_mul_f32_e32 v11, v11, v81
	v_cvt_pk_bf16_f32 v11, v11, v193
	ds_write_b16 v66, v11 offset:4864
	v_mul_f32_e32 v59, v59, v81
	v_cvt_pk_bf16_f32 v59, v59, v193
	ds_write_b16 v66, v59 offset:4928
	v_mul_f32_e32 v43, v43, v81
	v_cvt_pk_bf16_f32 v43, v43, v193
	ds_write_b16 v66, v43 offset:4992
	v_mul_f32_e32 v27, v27, v81
	v_cvt_pk_bf16_f32 v27, v27, v193
	ds_write_b16 v66, v27 offset:5056
	s_waitcnt lgkmcnt(7)
	v_mul_f32_e32 v12, v12, v82
	v_cvt_pk_bf16_f32 v12, v12, v193
	ds_write_b16 v66, v12 offset:6144
	v_mul_f32_e32 v60, v60, v82
	v_cvt_pk_bf16_f32 v60, v60, v193
	ds_write_b16 v66, v60 offset:6208
	v_mul_f32_e32 v44, v44, v82
	v_cvt_pk_bf16_f32 v44, v44, v193
	ds_write_b16 v66, v44 offset:6272
	v_mul_f32_e32 v28, v28, v82
	v_cvt_pk_bf16_f32 v28, v28, v193
	ds_write_b16 v66, v28 offset:6336
	v_mul_f32_e32 v13, v13, v83
	v_cvt_pk_bf16_f32 v13, v13, v193
	ds_write_b16 v66, v13 offset:6400
	v_mul_f32_e32 v61, v61, v83
	v_cvt_pk_bf16_f32 v61, v61, v193
	ds_write_b16 v66, v61 offset:6464
	v_mul_f32_e32 v45, v45, v83
	v_cvt_pk_bf16_f32 v45, v45, v193
	ds_write_b16 v66, v45 offset:6528
	v_mul_f32_e32 v29, v29, v83
	v_cvt_pk_bf16_f32 v29, v29, v193
	ds_write_b16 v66, v29 offset:6592
	s_waitcnt lgkmcnt(7)
	v_mul_f32_e32 v14, v14, v84
	v_cvt_pk_bf16_f32 v14, v14, v193
	ds_write_b16 v66, v14 offset:6656
	v_mul_f32_e32 v62, v62, v84
	v_cvt_pk_bf16_f32 v62, v62, v193
	ds_write_b16 v66, v62 offset:6720
	v_mul_f32_e32 v46, v46, v84
	v_cvt_pk_bf16_f32 v46, v46, v193
	ds_write_b16 v66, v46 offset:6784
	v_mul_f32_e32 v30, v30, v84
	v_cvt_pk_bf16_f32 v30, v30, v193
	ds_write_b16 v66, v30 offset:6848
	v_mul_f32_e32 v15, v15, v85
	v_cvt_pk_bf16_f32 v15, v15, v193
	ds_write_b16 v66, v15 offset:6912
	v_mul_f32_e32 v63, v63, v85
	v_cvt_pk_bf16_f32 v63, v63, v193
	ds_write_b16 v66, v63 offset:6976
	v_mul_f32_e32 v47, v47, v85
	v_cvt_pk_bf16_f32 v47, v47, v193
	ds_write_b16 v66, v47 offset:7040
	v_mul_f32_e32 v31, v31, v85
	v_cvt_pk_bf16_f32 v31, v31, v193
	ds_write_b16 v66, v31 offset:7104
	v_lshrrev_b32_e32 v64, 4, v177
	v_and_b32_e32 v65, 15, v177
	v_lshlrev_b32_e32 v66, 8, v178
	v_lshl_add_u32 v66, v64, 8, v66
	v_lshl_add_u32 v66, v65, 4, v66
	v_add_u32_e32 v66, 0x11000, v66
	v_add_u32_e32 v68, v178, v64
	v_mov_b32_e32 v69, 0
	v_lshlrev_b64 v[68:69], 11, v[68:69]
	v_lshl_add_u64 v[68:69], s[4:5], 0, v[68:69]
	v_lshlrev_b32_e32 v70, 4, v65
	v_mov_b32_e32 v71, 0
	v_lshl_add_u64 v[68:69], v[68:69], 0, v[70:71]
	s_waitcnt lgkmcnt(0)
	ds_read_b128 v[0:3], v66 offset:0
	ds_read_b128 v[4:7], v66 offset:1024
	ds_read_b128 v[8:11], v66 offset:2048
	ds_read_b128 v[12:15], v66 offset:3072
	ds_read_b128 v[16:19], v66 offset:4096
	ds_read_b128 v[20:23], v66 offset:5120
	ds_read_b128 v[24:27], v66 offset:6144
	ds_read_b128 v[28:31], v66 offset:7168
	s_waitcnt lgkmcnt(7)
	global_store_dwordx4 v[68:69], v[0:3], off offset:1024
	v_add_co_u32_e32 v68, vcc, 0x2000, v68
	s_nop 1
	v_addc_co_u32_e32 v69, vcc, 0, v69, vcc
	s_waitcnt lgkmcnt(6)
	global_store_dwordx4 v[68:69], v[4:7], off offset:1024
	v_add_co_u32_e32 v68, vcc, 0x2000, v68
	s_nop 1
	v_addc_co_u32_e32 v69, vcc, 0, v69, vcc
	s_waitcnt lgkmcnt(5)
	global_store_dwordx4 v[68:69], v[8:11], off offset:1024
	v_add_co_u32_e32 v68, vcc, 0x2000, v68
	s_nop 1
	v_addc_co_u32_e32 v69, vcc, 0, v69, vcc
	s_waitcnt lgkmcnt(4)
	global_store_dwordx4 v[68:69], v[12:15], off offset:1024
	v_add_co_u32_e32 v68, vcc, 0x2000, v68
	s_nop 1
	v_addc_co_u32_e32 v69, vcc, 0, v69, vcc
	s_waitcnt lgkmcnt(3)
	global_store_dwordx4 v[68:69], v[16:19], off offset:1024
	v_add_co_u32_e32 v68, vcc, 0x2000, v68
	s_nop 1
	v_addc_co_u32_e32 v69, vcc, 0, v69, vcc
	s_waitcnt lgkmcnt(2)
	global_store_dwordx4 v[68:69], v[20:23], off offset:1024
	v_add_co_u32_e32 v68, vcc, 0x2000, v68
	s_nop 1
	v_addc_co_u32_e32 v69, vcc, 0, v69, vcc
	s_waitcnt lgkmcnt(1)
	global_store_dwordx4 v[68:69], v[24:27], off offset:1024
	v_add_co_u32_e32 v68, vcc, 0x2000, v68
	s_nop 1
	v_addc_co_u32_e32 v69, vcc, 0, v69, vcc
	s_waitcnt lgkmcnt(0)
	global_store_dwordx4 v[68:69], v[28:31], off offset:1024
	s_branch .Lattn_epi_pad_end
	s_nop 0
	s_nop 0
	s_nop 0
	s_nop 0
	s_nop 0
	s_nop 0
	s_nop 0
	s_nop 0
	s_nop 0
	s_nop 0
	s_nop 0
	s_nop 0
	s_nop 0
	s_nop 0
	s_nop 0
	s_nop 0
	s_nop 0
	s_nop 0
	s_nop 0
	s_nop 0
	s_nop 0
	s_nop 0
	s_nop 0
	s_nop 0
	s_nop 0
	s_nop 0
	s_nop 0
	s_nop 0
	s_nop 0
	s_nop 0
	s_nop 0
	s_nop 0
	s_nop 0
	s_nop 0
	s_nop 0
	s_nop 0
	s_nop 0
	s_nop 0
	s_nop 0
	s_nop 0
	s_nop 0
	s_nop 0
	s_nop 0
	s_nop 0
	s_nop 0
	s_nop 0
	s_nop 0
	s_nop 0
	s_nop 0
	s_nop 0
	s_nop 0
	s_nop 0
	s_nop 0
	s_nop 0
	s_nop 0
	s_nop 0
	s_nop 0
	s_nop 0
	s_nop 0
	s_nop 0
	s_nop 0
	s_nop 0
	s_nop 0
	s_nop 0
	s_nop 0
	s_nop 0
	s_nop 0
	s_nop 0
	s_nop 0
	s_nop 0
	s_nop 0
	s_nop 0
	s_nop 0
	s_nop 0
	s_nop 0
	s_nop 0
	s_nop 0
	s_nop 0
	s_nop 0
	s_nop 0
	s_nop 0
	s_nop 0
	s_nop 0
	s_nop 0
	s_nop 0
	s_nop 0
	s_nop 0
	s_nop 0
	s_nop 0
	s_nop 0
	s_nop 0
.Lattn_epi_pad_end:
	s_mul_i32 s4, s31, s82
	s_add_i32 s14, s4, s6
	s_cmpk_lt_i32 s14, 0x480
	s_cbranch_scc0 .LBB0_358

.LBB0_640:
	s_xor_b64 s[0:1], s[42:43], -1
	s_xor_b64 s[48:49], s[6:7], -1
	s_andn2_b64 vcc, exec, s[40:41]
	v_readlane_b32 s93, v254, 11
	s_cbranch_vccnz .LBB0_852
	s_lshl_b32 vcc_hi, 1, s93
	s_and_b32 vcc_hi, vcc_hi, 0x80100
	s_cbranch_scc0 .Lstag_done
	v_readlane_b32 vcc_lo, v254, 41
	s_nop 4
	s_lshr_b32 vcc_lo, vcc_lo, 0
	s_and_b32 vcc_lo, vcc_lo, 7
	s_cbranch_scc0 .Lstag_done
	s_mul_i32 vcc_lo, vcc_lo, 1
.Lstag_loop:
	s_sleep 48
	s_add_i32 vcc_lo, vcc_lo, -1
	s_cmp_lg_u32 vcc_lo, 0
	s_cbranch_scc1 .Lstag_loop
.Lstag_done:
	s_nop 0
	s_waitcnt vmcnt(0)
	v_bfe_i32 v1, v176, 27, 1
	s_waitcnt vmcnt(6)
	v_lshlrev_b32_e32 v5, 4, v176
	v_lshrrev_b32_e32 v1, 22, v1
	v_add_u32_e32 v1, v5, v1
	v_and_b32_e32 v1, 0xfffffc00, v1
	v_sub_u32_e32 v1, v5, v1
	v_ashrrev_i32_e32 v0, 31, v176
	v_lshrrev_b32_e32 v2, 4, v1
	v_lshrrev_b32_e32 v0, 26, v0
	v_bitop3_b32 v1, v2, v1, 32 bitop3:0x6c
	v_add_u32_e32 v0, v176, v0
	v_ashrrev_i32_e32 v3, 31, v1
	v_ashrrev_i32_e32 v0, 6, v0
	v_lshrrev_b32_e32 v3, 26, v3
	v_lshlrev_b32_e32 v2, 3, v0
	v_add_u32_e32 v3, v1, v3
	v_and_b32_e32 v2, -16, v2
	v_ashrrev_i32_e32 v3, 6, v3
	v_add_u32_e32 v2, v3, v2
	v_readfirstlane_b32 s7, v176
	s_and_b64 vcc, exec, s[0:1]
	v_mov_b32_e32 v4, v2
	s_cbranch_vccz .LBB0_643
	v_lshlrev_b32_e32 v4, 1, v2
	v_lshrrev_b32_e32 v6, 2, v2
	v_and_b32_e32 v7, 3, v3
	s_movk_i32 s2, 0xffe0
	v_and_b32_e32 v4, 24, v4
	v_and_b32_e32 v6, 4, v6
	v_and_or_b32 v7, v2, s2, v7
	v_or3_b32 v4, v7, v6, v4
